# weight-conversion item loop fully unrolled: all 32 loads of an item issued before the first wait (was two serial batches of 16)
# speedup vs baseline: 1.0020x; 1.0020x over previous
; #define LAS __attribute__((address_space(3)))
; __device__ __forceinline__ void transpose_item(const float* W, int K, int N, bf16* WT, int k0, int n0, int drow0, LAS float* scr, int lane) {
; #pragma unroll 8
;     for (int i = 0; i < 32; ++i) { const int kk = 2 * i + (lane >> 5); scr[kk * 33 + (lane & 31)] = W[(size_t)(k0 + kk) * N + n0 + (lane & 31)]; }
.LBB0_35:
	s_lshl_b32 s45, s35, 1
	s_lshl_b32 s46, s40, 1
	v_or_b32_e32 v15, s45, v1
	v_or_b32_e32 v19, s46, v2
	s_add_i32 s47, s45, 4
	s_add_i32 s48, s46, 4
	s_add_i32 s49, s45, 8
	s_add_i32 s50, s46, 8
	s_add_i32 s51, s45, 12
	s_add_i32 s54, s46, 12
	s_add_i32 s55, s45, 16
	s_add_i32 s56, s46, 16
	s_add_i32 s57, s45, 20
	s_add_i32 s58, s46, 20
	s_add_i32 s59, s45, 24
	s_add_i32 s60, s46, 24
	s_add_i32 s45, s45, 28
	s_add_i32 s46, s46, 28
	v_add_u32_e32 v16, s37, v15
	v_add_u32_e32 v20, s34, v19
	v_or_b32_e32 v79, s47, v1
	v_or_b32_e32 v81, s48, v2
	v_or_b32_e32 v82, s49, v1
	v_or_b32_e32 v83, s50, v2
	v_or_b32_e32 v84, s51, v1
	v_or_b32_e32 v85, s54, v2
	v_or_b32_e32 v86, s55, v1
	v_or_b32_e32 v87, s56, v2
	v_or_b32_e32 v88, s57, v1
	v_or_b32_e32 v89, s58, v2
	v_or_b32_e32 v90, s59, v1
	v_or_b32_e32 v91, s60, v2
	v_or_b32_e32 v92, s45, v1
	v_or_b32_e32 v93, s46, v2
	v_ashrrev_i32_e32 v25, 31, v20
	v_ashrrev_i32_e32 v23, 31, v16
	v_mad_u64_u32 v[16:17], s[46:47], s38, v16, 0
	v_mad_u64_u32 v[20:21], s[46:47], s44, v20, 0
	v_add_u32_e32 v26, s37, v79
	v_add_u32_e32 v28, s34, v81
	v_add_u32_e32 v30, s37, v82
	v_add_u32_e32 v32, s34, v83
	v_add_u32_e32 v34, s37, v84
	v_add_u32_e32 v36, s34, v85
	v_add_u32_e32 v38, s37, v86
	v_add_u32_e32 v40, s34, v87
	v_add_u32_e32 v42, s37, v88
	v_add_u32_e32 v44, s34, v89
	v_add_u32_e32 v46, s37, v90
	v_add_u32_e32 v48, s34, v91
	v_add_u32_e32 v50, s37, v92
	v_add_u32_e32 v52, s34, v93
	v_mov_b32_e32 v22, v17
	v_mov_b32_e32 v24, v21
	v_ashrrev_i32_e32 v55, 31, v28
	v_ashrrev_i32_e32 v57, 31, v26
	v_mad_u64_u32 v[26:27], s[46:47], s38, v26, 0
	v_mad_u64_u32 v[28:29], s[46:47], s44, v28, 0
	v_ashrrev_i32_e32 v59, 31, v32
	v_ashrrev_i32_e32 v61, 31, v30
	v_mad_u64_u32 v[30:31], s[46:47], s38, v30, 0
	v_mad_u64_u32 v[32:33], s[46:47], s44, v32, 0
	v_ashrrev_i32_e32 v63, 31, v36
	v_ashrrev_i32_e32 v65, 31, v34
	v_mad_u64_u32 v[34:35], s[46:47], s38, v34, 0
	v_mad_u64_u32 v[36:37], s[46:47], s44, v36, 0
	v_ashrrev_i32_e32 v67, 31, v40
	v_ashrrev_i32_e32 v69, 31, v38
	v_mad_u64_u32 v[38:39], s[46:47], s38, v38, 0
	v_mad_u64_u32 v[40:41], s[46:47], s44, v40, 0
	v_ashrrev_i32_e32 v71, 31, v44
	v_ashrrev_i32_e32 v73, 31, v42
	v_mad_u64_u32 v[42:43], s[46:47], s38, v42, 0
	v_mad_u64_u32 v[44:45], s[46:47], s44, v44, 0
	v_ashrrev_i32_e32 v75, 31, v48
	v_ashrrev_i32_e32 v77, 31, v46
	v_mad_u64_u32 v[46:47], s[46:47], s38, v46, 0
	v_mad_u64_u32 v[48:49], s[46:47], s44, v48, 0
	v_ashrrev_i32_e32 v94, 31, v52
	v_ashrrev_i32_e32 v95, 31, v50
	v_mad_u64_u32 v[50:51], s[46:47], s38, v50, 0
	v_mad_u64_u32 v[52:53], s[46:47], s44, v52, 0
	v_mad_u64_u32 v[22:23], s[46:47], s38, v23, v[22:23]
	v_mad_u64_u32 v[24:25], s[46:47], s44, v25, v[24:25]
	v_mov_b32_e32 v54, v27
	v_mov_b32_e32 v56, v29
	v_mov_b32_e32 v58, v31
	v_mov_b32_e32 v60, v33
	v_mov_b32_e32 v62, v35
	v_mov_b32_e32 v64, v37
	v_mov_b32_e32 v66, v39
	v_mov_b32_e32 v68, v41
	v_mov_b32_e32 v70, v43
	v_mov_b32_e32 v72, v45
	v_mov_b32_e32 v74, v47
	v_mov_b32_e32 v76, v49
	v_mov_b32_e32 v78, v51
	v_mov_b32_e32 v80, v53
	v_mov_b32_e32 v17, v22
	v_mov_b32_e32 v21, v24
	v_mad_u64_u32 v[22:23], s[46:47], s38, v57, v[54:55]
	v_mad_u64_u32 v[24:25], s[46:47], s44, v55, v[56:57]
	v_mad_u64_u32 v[54:55], s[46:47], s38, v61, v[58:59]
	v_mad_u64_u32 v[56:57], s[46:47], s44, v59, v[60:61]
	v_mad_u64_u32 v[58:59], s[46:47], s38, v65, v[62:63]
	v_mad_u64_u32 v[60:61], s[46:47], s44, v63, v[64:65]
	v_mad_u64_u32 v[62:63], s[46:47], s38, v69, v[66:67]
	v_mad_u64_u32 v[64:65], s[46:47], s44, v67, v[68:69]
	v_mad_u64_u32 v[66:67], s[46:47], s38, v73, v[70:71]
	v_mad_u64_u32 v[68:69], s[46:47], s44, v71, v[72:73]
	v_mad_u64_u32 v[70:71], s[46:47], s38, v77, v[74:75]
	v_mad_u64_u32 v[72:73], s[46:47], s44, v75, v[76:77]
	v_mad_u64_u32 v[74:75], s[46:47], s38, v95, v[78:79]
	v_mad_u64_u32 v[76:77], s[46:47], s44, v94, v[80:81]
	v_mov_b32_e32 v27, v22
	v_mov_b32_e32 v29, v24
	v_mov_b32_e32 v31, v54
	v_mov_b32_e32 v33, v56
	v_mov_b32_e32 v35, v58
	v_mov_b32_e32 v37, v60
	v_mov_b32_e32 v39, v62
	v_mov_b32_e32 v41, v64
	v_mov_b32_e32 v43, v66
	v_mov_b32_e32 v45, v68
	v_mov_b32_e32 v47, v70
	v_mov_b32_e32 v49, v72
	v_lshl_add_u64 v[20:21], v[20:21], 2, v[10:11]
	v_mov_b32_e32 v51, v74
	v_mov_b32_e32 v53, v76
	v_lshl_add_u64 v[16:17], v[16:17], 2, v[10:11]
	v_lshl_add_u64 v[22:23], v[28:29], 2, v[10:11]
	v_lshl_add_u64 v[24:25], v[26:27], 2, v[10:11]
	v_lshl_add_u64 v[26:27], v[32:33], 2, v[10:11]
	v_lshl_add_u64 v[28:29], v[30:31], 2, v[10:11]
	v_lshl_add_u64 v[30:31], v[36:37], 2, v[10:11]
	v_lshl_add_u64 v[32:33], v[34:35], 2, v[10:11]
	v_lshl_add_u64 v[34:35], v[40:41], 2, v[10:11]
	v_lshl_add_u64 v[36:37], v[38:39], 2, v[10:11]
	v_lshl_add_u64 v[38:39], v[44:45], 2, v[10:11]
	v_lshl_add_u64 v[40:41], v[42:43], 2, v[10:11]
	v_lshl_add_u64 v[42:43], v[48:49], 2, v[10:11]
	v_lshl_add_u64 v[44:45], v[46:47], 2, v[10:11]
	v_lshl_add_u64 v[46:47], v[52:53], 2, v[10:11]
	v_lshl_add_u64 v[48:49], v[50:51], 2, v[10:11]
	global_load_dword v50, v[20:21], off
	global_load_dword v51, v[16:17], off
	global_load_dword v52, v[22:23], off
	global_load_dword v53, v[24:25], off
	global_load_dword v54, v[26:27], off
	global_load_dword v55, v[28:29], off
	global_load_dword v56, v[30:31], off
	global_load_dword v57, v[32:33], off
	global_load_dword v58, v[34:35], off
	global_load_dword v59, v[36:37], off
	global_load_dword v60, v[38:39], off
	global_load_dword v61, v[40:41], off
	global_load_dword v62, v[42:43], off
	global_load_dword v63, v[44:45], off
	global_load_dword v64, v[46:47], off
	global_load_dword v65, v[48:49], off
	s_add_i32 s40, s40, 16
	s_add_i32 s35, s35, 16
	s_lshl_b32 s45, s35, 1
; #define LAS __attribute__((address_space(3)))
; __device__ __forceinline__ void transpose_item(const float* W, int K, int N, bf16* WT, int k0, int n0, int drow0, LAS float* scr, int lane) {
; #pragma unroll 8
;     for (int i = 0; i < 32; ++i) { const int kk = 2 * i + (lane >> 5); scr[kk * 33 + (lane & 31)] = W[(size_t)(k0 + kk) * N + n0 + (lane & 31)]; }
	s_lshl_b32 s46, s40, 1
	v_or_b32_e32 v145, s45, v1
	v_or_b32_e32 v149, s46, v2
	s_add_i32 s47, s45, 4
	s_add_i32 s48, s46, 4
	s_add_i32 s49, s45, 8
	s_add_i32 s50, s46, 8
	s_add_i32 s51, s45, 12
	s_add_i32 s54, s46, 12
	s_add_i32 s55, s45, 16
	s_add_i32 s56, s46, 16
	s_add_i32 s57, s45, 20
	s_add_i32 s58, s46, 20
	s_add_i32 s59, s45, 24
	s_add_i32 s60, s46, 24
	s_add_i32 s45, s45, 28
	s_add_i32 s46, s46, 28
	v_add_u32_e32 v146, s37, v145
	v_add_u32_e32 v150, s34, v149
	v_or_b32_e32 v209, s47, v1
	v_or_b32_e32 v211, s48, v2
	v_or_b32_e32 v212, s49, v1
	v_or_b32_e32 v213, s50, v2
	v_or_b32_e32 v214, s51, v1
	v_or_b32_e32 v215, s54, v2
	v_or_b32_e32 v216, s55, v1
	v_or_b32_e32 v217, s56, v2
	v_or_b32_e32 v218, s57, v1
	v_or_b32_e32 v219, s58, v2
	v_or_b32_e32 v220, s59, v1
	v_or_b32_e32 v221, s60, v2
	v_or_b32_e32 v222, s45, v1
	v_or_b32_e32 v223, s46, v2
	v_ashrrev_i32_e32 v155, 31, v150
	v_ashrrev_i32_e32 v153, 31, v146
	v_mad_u64_u32 v[146:147], s[46:47], s38, v146, 0
	v_mad_u64_u32 v[150:151], s[46:47], s44, v150, 0
	v_add_u32_e32 v156, s37, v209
	v_add_u32_e32 v158, s34, v211
	v_add_u32_e32 v160, s37, v212
	v_add_u32_e32 v162, s34, v213
	v_add_u32_e32 v164, s37, v214
	v_add_u32_e32 v166, s34, v215
	v_add_u32_e32 v168, s37, v216
	v_add_u32_e32 v170, s34, v217
	v_add_u32_e32 v172, s37, v218
	v_add_u32_e32 v174, s34, v219
	v_add_u32_e32 v176, s37, v220
	v_add_u32_e32 v178, s34, v221
	v_add_u32_e32 v180, s37, v222
	v_add_u32_e32 v182, s34, v223
	v_mov_b32_e32 v152, v147
	v_mov_b32_e32 v154, v151
	v_ashrrev_i32_e32 v185, 31, v158
	v_ashrrev_i32_e32 v187, 31, v156
	v_mad_u64_u32 v[156:157], s[46:47], s38, v156, 0
	v_mad_u64_u32 v[158:159], s[46:47], s44, v158, 0
	v_ashrrev_i32_e32 v189, 31, v162
	v_ashrrev_i32_e32 v191, 31, v160
	v_mad_u64_u32 v[160:161], s[46:47], s38, v160, 0
	v_mad_u64_u32 v[162:163], s[46:47], s44, v162, 0
	v_ashrrev_i32_e32 v193, 31, v166
	v_ashrrev_i32_e32 v195, 31, v164
	v_mad_u64_u32 v[164:165], s[46:47], s38, v164, 0
	v_mad_u64_u32 v[166:167], s[46:47], s44, v166, 0
	v_ashrrev_i32_e32 v197, 31, v170
	v_ashrrev_i32_e32 v199, 31, v168
	v_mad_u64_u32 v[168:169], s[46:47], s38, v168, 0
	v_mad_u64_u32 v[170:171], s[46:47], s44, v170, 0
	v_ashrrev_i32_e32 v201, 31, v174
	v_ashrrev_i32_e32 v203, 31, v172
	v_mad_u64_u32 v[172:173], s[46:47], s38, v172, 0
	v_mad_u64_u32 v[174:175], s[46:47], s44, v174, 0
	v_ashrrev_i32_e32 v205, 31, v178
	v_ashrrev_i32_e32 v207, 31, v176
	v_mad_u64_u32 v[176:177], s[46:47], s38, v176, 0
	v_mad_u64_u32 v[178:179], s[46:47], s44, v178, 0
	v_ashrrev_i32_e32 v224, 31, v182
	v_ashrrev_i32_e32 v225, 31, v180
	v_mad_u64_u32 v[180:181], s[46:47], s38, v180, 0
	v_mad_u64_u32 v[182:183], s[46:47], s44, v182, 0
	v_mad_u64_u32 v[152:153], s[46:47], s38, v153, v[152:153]
	v_mad_u64_u32 v[154:155], s[46:47], s44, v155, v[154:155]
	v_mov_b32_e32 v184, v157
	v_mov_b32_e32 v186, v159
	v_mov_b32_e32 v188, v161
	v_mov_b32_e32 v190, v163
	v_mov_b32_e32 v192, v165
	v_mov_b32_e32 v194, v167
	v_mov_b32_e32 v196, v169
	v_mov_b32_e32 v198, v171
	v_mov_b32_e32 v200, v173
	v_mov_b32_e32 v202, v175
	v_mov_b32_e32 v204, v177
	v_mov_b32_e32 v206, v179
	v_mov_b32_e32 v208, v181
	v_mov_b32_e32 v210, v183
	v_mov_b32_e32 v147, v152
	v_mov_b32_e32 v151, v154
	v_mad_u64_u32 v[152:153], s[46:47], s38, v187, v[184:185]
	v_mad_u64_u32 v[154:155], s[46:47], s44, v185, v[186:187]
	v_mad_u64_u32 v[184:185], s[46:47], s38, v191, v[188:189]
	v_mad_u64_u32 v[186:187], s[46:47], s44, v189, v[190:191]
	v_mad_u64_u32 v[188:189], s[46:47], s38, v195, v[192:193]
	v_mad_u64_u32 v[190:191], s[46:47], s44, v193, v[194:195]
	v_mad_u64_u32 v[192:193], s[46:47], s38, v199, v[196:197]
	v_mad_u64_u32 v[194:195], s[46:47], s44, v197, v[198:199]
	v_mad_u64_u32 v[196:197], s[46:47], s38, v203, v[200:201]
	v_mad_u64_u32 v[198:199], s[46:47], s44, v201, v[202:203]
	v_mad_u64_u32 v[200:201], s[46:47], s38, v207, v[204:205]
	v_mad_u64_u32 v[202:203], s[46:47], s44, v205, v[206:207]
	v_mad_u64_u32 v[204:205], s[46:47], s38, v225, v[208:209]
	v_mad_u64_u32 v[206:207], s[46:47], s44, v224, v[210:211]
	v_mov_b32_e32 v157, v152
	v_mov_b32_e32 v159, v154
	v_mov_b32_e32 v161, v184
	v_mov_b32_e32 v163, v186
	v_mov_b32_e32 v165, v188
	v_mov_b32_e32 v167, v190
	v_mov_b32_e32 v169, v192
	v_mov_b32_e32 v171, v194
	v_mov_b32_e32 v173, v196
	v_mov_b32_e32 v175, v198
	v_mov_b32_e32 v177, v200
	v_mov_b32_e32 v179, v202
	v_lshl_add_u64 v[150:151], v[150:151], 2, v[10:11]
	v_mov_b32_e32 v181, v204
	v_mov_b32_e32 v183, v206
	v_lshl_add_u64 v[146:147], v[146:147], 2, v[10:11]
	v_lshl_add_u64 v[152:153], v[158:159], 2, v[10:11]
	v_lshl_add_u64 v[154:155], v[156:157], 2, v[10:11]
	v_lshl_add_u64 v[156:157], v[162:163], 2, v[10:11]
	v_lshl_add_u64 v[158:159], v[160:161], 2, v[10:11]
	v_lshl_add_u64 v[160:161], v[166:167], 2, v[10:11]
	v_lshl_add_u64 v[162:163], v[164:165], 2, v[10:11]
	v_lshl_add_u64 v[164:165], v[170:171], 2, v[10:11]
	v_lshl_add_u64 v[166:167], v[168:169], 2, v[10:11]
	v_lshl_add_u64 v[168:169], v[174:175], 2, v[10:11]
	v_lshl_add_u64 v[170:171], v[172:173], 2, v[10:11]
	v_lshl_add_u64 v[172:173], v[178:179], 2, v[10:11]
	v_lshl_add_u64 v[174:175], v[176:177], 2, v[10:11]
	v_lshl_add_u64 v[176:177], v[182:183], 2, v[10:11]
	v_lshl_add_u64 v[178:179], v[180:181], 2, v[10:11]
	global_load_dword v180, v[150:151], off
	global_load_dword v181, v[146:147], off
	global_load_dword v182, v[152:153], off
	global_load_dword v183, v[154:155], off
	global_load_dword v184, v[156:157], off
	global_load_dword v185, v[158:159], off
	global_load_dword v186, v[160:161], off
	global_load_dword v187, v[162:163], off
	global_load_dword v188, v[164:165], off
; __device__ __forceinline__ unsigned cvt_pk_bf16(float lo, float hi) { f32x2_t v = {lo, hi}; bf16x2_t b = __builtin_convertvector(v, bf16x2_t); return __builtin_bit_cast(unsigned, b); }
; #define LAS __attribute__((address_space(3)))
; __device__ __forceinline__ float rnd6(float f) { unsigned u = __float_as_uint(f); u += 0xffffu + ((u >> 17) & 1u); u &= 0xfffe0000u; return __uint_as_float(u); }
; __device__ __forceinline__ void transpose_item(const float* W, int K, int N, bf16* WT, int k0, int n0, int drow0, LAS float* scr, int lane) {
;     ...
;     for (int i = 0; i < 32; ++i) { const int kk = 2 * i + (lane >> 5); scr[kk * 33 + (lane & 31)] = W[(size_t)(k0 + kk) * N + n0 + (lane & 31)]; }
;     asm volatile("s_waitcnt lgkmcnt(0)" ::: "memory");
;     const int c = lane & 7;
; #pragma unroll
;     for (int j = 0; j < 4; ++j) { const int n = (lane >> 3) + 8 * j; const LAS float* s = scr + (8 * c) * 33 + n;
;         u32x4 o; o.x = cvt_pk_bf16(rnd6(s[0 * 33]), rnd6(s[1 * 33])); o.y = cvt_pk_bf16(rnd6(s[2 * 33]), rnd6(s[3 * 33])); o.z = cvt_pk_bf16(rnd6(s[4 * 33]), rnd6(s[5 * 33])); o.w = cvt_pk_bf16(rnd6(s[6 * 33]), rnd6(s[7 * 33]));
	global_load_dword v189, v[166:167], off
	global_load_dword v190, v[168:169], off
	global_load_dword v191, v[170:171], off
	global_load_dword v192, v[172:173], off
	global_load_dword v193, v[174:175], off
	global_load_dword v194, v[176:177], off
	global_load_dword v195, v[178:179], off
	s_add_i32 s40, s40, 16
	s_add_i32 s35, s35, 16
	s_mov_b32 s39, 0
	v_mad_u64_u32 v[16:17], s[46:47], v19, s4, v[6:7]
	v_mad_u64_u32 v[20:21], s[46:47], v15, s4, v[6:7]
	v_mad_u64_u32 v[22:23], s[46:47], v81, s4, v[6:7]
	v_mad_u64_u32 v[24:25], s[46:47], v79, s4, v[6:7]
	v_mad_u64_u32 v[26:27], s[46:47], v83, s4, v[6:7]
	v_mad_u64_u32 v[28:29], s[46:47], v82, s4, v[6:7]
	v_mad_u64_u32 v[30:31], s[46:47], v85, s4, v[6:7]
	v_mad_u64_u32 v[32:33], s[46:47], v84, s4, v[6:7]
	v_mad_u64_u32 v[34:35], s[46:47], v87, s4, v[6:7]
	v_mad_u64_u32 v[36:37], s[46:47], v86, s4, v[6:7]
	v_mad_u64_u32 v[38:39], s[46:47], v89, s4, v[6:7]
	v_mad_u64_u32 v[40:41], s[46:47], v88, s4, v[6:7]
	v_mad_u64_u32 v[42:43], s[46:47], v91, s4, v[6:7]
	v_mad_u64_u32 v[44:45], s[46:47], v90, s4, v[6:7]
	v_mad_u64_u32 v[46:47], s[46:47], v93, s4, v[6:7]
	v_mad_u64_u32 v[48:49], s[46:47], v92, s4, v[6:7]
	v_mad_u64_u32 v[146:147], s[46:47], v149, s4, v[6:7]
	v_mad_u64_u32 v[150:151], s[46:47], v145, s4, v[6:7]
	v_mad_u64_u32 v[152:153], s[46:47], v211, s4, v[6:7]
	v_mad_u64_u32 v[154:155], s[46:47], v209, s4, v[6:7]
	v_mad_u64_u32 v[156:157], s[46:47], v213, s4, v[6:7]
	v_mad_u64_u32 v[158:159], s[46:47], v212, s4, v[6:7]
	v_mad_u64_u32 v[160:161], s[46:47], v215, s4, v[6:7]
	v_mad_u64_u32 v[162:163], s[46:47], v214, s4, v[6:7]
	v_mad_u64_u32 v[164:165], s[46:47], v217, s4, v[6:7]
	v_mad_u64_u32 v[166:167], s[46:47], v216, s4, v[6:7]
	v_mad_u64_u32 v[168:169], s[46:47], v219, s4, v[6:7]
	v_mad_u64_u32 v[170:171], s[46:47], v218, s4, v[6:7]
	v_mad_u64_u32 v[172:173], s[46:47], v221, s4, v[6:7]
	v_mad_u64_u32 v[174:175], s[46:47], v220, s4, v[6:7]
	v_mad_u64_u32 v[176:177], s[46:47], v223, s4, v[6:7]
	v_mad_u64_u32 v[178:179], s[46:47], v222, s4, v[6:7]
	s_waitcnt vmcnt(31)
	ds_write_b32 v16, v50
	s_waitcnt vmcnt(30)
	ds_write_b32 v20, v51
	s_waitcnt vmcnt(29)
	ds_write_b32 v22, v52
	s_waitcnt vmcnt(28)
	ds_write_b32 v24, v53
	s_waitcnt vmcnt(27)
	ds_write_b32 v26, v54
	s_waitcnt vmcnt(26)
	ds_write_b32 v28, v55
	s_waitcnt vmcnt(25)
	ds_write_b32 v30, v56
	s_waitcnt vmcnt(24)
	ds_write_b32 v32, v57
	s_waitcnt vmcnt(23)
	ds_write_b32 v34, v58
	s_waitcnt vmcnt(22)
	ds_write_b32 v36, v59
	s_waitcnt vmcnt(21)
	ds_write_b32 v38, v60
	s_waitcnt vmcnt(20)
	ds_write_b32 v40, v61
	s_waitcnt vmcnt(19)
	ds_write_b32 v42, v62
	s_waitcnt vmcnt(18)
	ds_write_b32 v44, v63
	s_waitcnt vmcnt(17)
	ds_write_b32 v46, v64
	s_waitcnt vmcnt(16)
	ds_write_b32 v48, v65
	s_waitcnt vmcnt(15)
	ds_write_b32 v146, v180
	s_waitcnt vmcnt(14)
	ds_write_b32 v150, v181
	s_waitcnt vmcnt(13)
	ds_write_b32 v152, v182
	s_waitcnt vmcnt(12)
	ds_write_b32 v154, v183
	s_waitcnt vmcnt(11)
	ds_write_b32 v156, v184
	s_waitcnt vmcnt(10)
	ds_write_b32 v158, v185
	s_waitcnt vmcnt(9)
	ds_write_b32 v160, v186
	s_waitcnt vmcnt(8)
	ds_write_b32 v162, v187
	s_waitcnt vmcnt(7)
	ds_write_b32 v164, v188
	s_waitcnt vmcnt(6)
	ds_write_b32 v166, v189
	s_waitcnt vmcnt(5)
	ds_write_b32 v168, v190
	s_waitcnt vmcnt(4)
	ds_write_b32 v170, v191
	s_waitcnt vmcnt(3)
	ds_write_b32 v172, v192
	s_waitcnt vmcnt(2)
	ds_write_b32 v174, v193
	s_waitcnt vmcnt(1)
	ds_write_b32 v176, v194
	s_waitcnt vmcnt(0)
	ds_write_b32 v178, v195
	s_cmp_lg_u32 s39, 0
	s_waitcnt lgkmcnt(0)
	ds_read2_b32 v[10:11], v7 offset1:8
	ds_read2_b32 v[16:17], v7 offset0:33 offset1:41
	ds_read2_b32 v[26:27], v7 offset0:66 offset1:74
	ds_read2_b32 v[28:29], v7 offset0:99 offset1:107
	ds_read2_b32 v[30:31], v7 offset0:132 offset1:140
	s_waitcnt lgkmcnt(4)
	v_bfe_u32 v15, v10, 17, 1
	v_add3_u32 v10, v10, v15, s5
	s_waitcnt lgkmcnt(3)
	v_bfe_u32 v15, v16, 17, 1
	v_add3_u32 v15, v16, v15, s5
	ds_read2_b32 v[32:33], v7 offset0:165 offset1:173
	v_and_b32_e32 v10, 0xfffe0000, v10
	v_and_b32_e32 v15, 0xfffe0000, v15
	v_cvt_pk_bf16_f32 v20, v10, v15
	s_waitcnt lgkmcnt(3)
	v_bfe_u32 v10, v26, 17, 1
	s_waitcnt lgkmcnt(2)
	v_bfe_u32 v15, v28, 17, 1
	v_add3_u32 v10, v26, v10, s5
	v_add3_u32 v15, v28, v15, s5
	ds_read2_b32 v[34:35], v7 offset0:198 offset1:206
	ds_read2_b32 v[36:37], v7 offset0:231 offset1:239
	s_lshl_b32 s35, s41, 6
	s_and_b32 s37, s36, 0x60
	v_and_b32_e32 v10, 0xfffe0000, v10
	v_and_b32_e32 v15, 0xfffe0000, v15
	s_or_b32 s37, s37, s43
	s_and_b32 s35, s35, 0xffffff00
	v_cvt_pk_bf16_f32 v21, v10, v15
	s_waitcnt lgkmcnt(3)
	v_bfe_u32 v10, v30, 17, 1
	s_waitcnt lgkmcnt(2)
	v_bfe_u32 v15, v32, 17, 1
	s_or_b32 s35, s37, s35
	v_add3_u32 v10, v30, v10, s5
	v_add3_u32 v15, v32, v15, s5
	s_and_b64 s[30:31], s[30:31], exec
	v_and_b32_e32 v10, 0xfffe0000, v10
	v_and_b32_e32 v15, 0xfffe0000, v15
	s_cselect_b32 s30, s36, s35
	s_ashr_i32 s35, s34, 31
	v_cvt_pk_bf16_f32 v22, v10, v15
	s_waitcnt lgkmcnt(1)
; __device__ __forceinline__ unsigned cvt_pk_bf16(float lo, float hi) { f32x2_t v = {lo, hi}; bf16x2_t b = __builtin_convertvector(v, bf16x2_t); return __builtin_bit_cast(unsigned, b); }
; #define LAS __attribute__((address_space(3)))
; __device__ __forceinline__ float rnd6(float f) { unsigned u = __float_as_uint(f); u += 0xffffu + ((u >> 17) & 1u); u &= 0xfffe0000u; return __uint_as_float(u); }
; __device__ __forceinline__ void transpose_item(const float* W, int K, int N, bf16* WT, int k0, int n0, int drow0, LAS float* scr, int lane) {
;     ...
;     const int c = lane & 7;
; #pragma unroll
;     for (int j = 0; j < 4; ++j) { const int n = (lane >> 3) + 8 * j; const LAS float* s = scr + (8 * c) * 33 + n;
;         u32x4 o; o.x = cvt_pk_bf16(rnd6(s[0 * 33]), rnd6(s[1 * 33])); o.y = cvt_pk_bf16(rnd6(s[2 * 33]), rnd6(s[3 * 33])); o.z = cvt_pk_bf16(rnd6(s[4 * 33]), rnd6(s[5 * 33])); o.w = cvt_pk_bf16(rnd6(s[6 * 33]), rnd6(s[7 * 33]));
;         *(u32x4*)(WT + (size_t)(drow0 + n) * K + k0 + 8 * c) = o; }
;     asm volatile("s_waitcnt lgkmcnt(0)" ::: "memory");
; }
; __device__ __forceinline__ void convert_weights(CArgs& a, LAS unsigned char* lds, int gw, int NGW, int wave, int lane) {
;     LAS float* scr = (LAS float*)(lds + wave * 16384);
;     constexpr int I_FFU = (D / 64) * (FF / 32), I_FFD = (FF / 64) * (D / 32), I_IN_ = (D / 64) * (DIN / 32), I_OUT_ = (D / 64) * (D / 32);
;     constexpr int PER_LAYER = 4 * I_FFU + 2 * I_FFD + I_IN_ + I_OUT_;
;     for (int it = gw; it < DEPTH * PER_LAYER; it += NGW) {
	v_bfe_u32 v10, v34, 17, 1
	s_waitcnt lgkmcnt(0)
	v_bfe_u32 v15, v36, 17, 1
	s_lshl_b64 s[34:35], s[34:35], 1
	v_add3_u32 v10, v34, v10, s5
	v_add3_u32 v15, v36, v15, s5
	s_add_u32 s28, s28, s34
	v_and_b32_e32 v10, 0xfffe0000, v10
	v_and_b32_e32 v15, 0xfffe0000, v15
	s_addc_u32 s29, s29, s35
	v_cvt_pk_bf16_f32 v23, v10, v15
	v_or_b32_e32 v10, s30, v3
	v_lshl_add_u64 v[24:25], s[28:29], 0, v[4:5]
	v_mad_u64_u32 v[38:39], s[28:29], s26, v10, 0
	v_mul_lo_u32 v15, s27, v10
	s_ashr_i32 s28, s30, 31
	v_bfe_u32 v10, v11, 17, 1
	s_mul_i32 s31, s26, s28
	v_add3_u32 v10, v11, v10, s5
	v_bfe_u32 v11, v17, 17, 1
	v_add3_u32 v39, v39, s31, v15
	v_add3_u32 v11, v17, v11, s5
	v_lshl_add_u64 v[38:39], v[38:39], 1, v[24:25]
	v_and_b32_e32 v10, 0xfffe0000, v10
	v_and_b32_e32 v11, 0xfffe0000, v11
	global_store_dwordx4 v[38:39], v[20:23], off
	ds_read2_b32 v[16:17], v7 offset0:16 offset1:24
	s_add_i32 s42, s42, s33
	v_cvt_pk_bf16_f32 v20, v10, v11
	v_bfe_u32 v10, v27, 17, 1
	v_bfe_u32 v11, v29, 17, 1
	v_add3_u32 v10, v27, v10, s5
	v_add3_u32 v11, v29, v11, s5
	v_and_b32_e32 v10, 0xfffe0000, v10
	v_and_b32_e32 v11, 0xfffe0000, v11
	v_cvt_pk_bf16_f32 v21, v10, v11
	v_bfe_u32 v10, v31, 17, 1
	v_bfe_u32 v11, v33, 17, 1
	v_add3_u32 v10, v31, v10, s5
	v_add3_u32 v11, v33, v11, s5
	v_and_b32_e32 v10, 0xfffe0000, v10
	v_and_b32_e32 v11, 0xfffe0000, v11
	v_cvt_pk_bf16_f32 v22, v10, v11
	v_bfe_u32 v10, v35, 17, 1
	v_bfe_u32 v11, v37, 17, 1
	v_add3_u32 v10, v35, v10, s5
	v_add3_u32 v11, v37, v11, s5
	v_and_b32_e32 v10, 0xfffe0000, v10
	v_and_b32_e32 v11, 0xfffe0000, v11
	v_cvt_pk_bf16_f32 v23, v10, v11
	v_or_b32_e32 v10, s30, v12
	v_mul_lo_u32 v15, s27, v10
	v_mad_u64_u32 v[10:11], s[28:29], s26, v10, 0
	v_add3_u32 v11, v11, s31, v15
	v_lshl_add_u64 v[10:11], v[10:11], 1, v[24:25]
	ds_read2_b32 v[26:27], v7 offset0:49 offset1:57
	global_store_dwordx4 v[10:11], v[20:23], off
	s_waitcnt lgkmcnt(1)
	v_bfe_u32 v10, v16, 17, 1
	v_add3_u32 v10, v16, v10, s5
	v_and_b32_e32 v15, 0xfffe0000, v10
	ds_read2_b32 v[10:11], v7 offset0:82 offset1:90
	ds_read2_b32 v[28:29], v7 offset0:115 offset1:123
	s_waitcnt lgkmcnt(2)
	v_bfe_u32 v16, v26, 17, 1
	v_add3_u32 v16, v26, v16, s5
	v_and_b32_e32 v16, 0xfffe0000, v16
	ds_read2_b32 v[30:31], v7 offset0:148 offset1:156
	ds_read2_b32 v[32:33], v7 offset0:181 offset1:189
	v_cvt_pk_bf16_f32 v20, v15, v16
	s_waitcnt lgkmcnt(3)
	v_bfe_u32 v15, v10, 17, 1
	v_add3_u32 v10, v10, v15, s5
	s_waitcnt lgkmcnt(2)
	v_bfe_u32 v15, v28, 17, 1
	v_add3_u32 v15, v28, v15, s5
	ds_read2_b32 v[34:35], v7 offset0:214 offset1:222
	ds_read2_b32 v[36:37], v7 offset0:247 offset1:255
	v_and_b32_e32 v10, 0xfffe0000, v10
	v_and_b32_e32 v15, 0xfffe0000, v15
	v_cvt_pk_bf16_f32 v21, v10, v15
	s_waitcnt lgkmcnt(3)
	v_bfe_u32 v10, v30, 17, 1
	s_waitcnt lgkmcnt(2)
	v_bfe_u32 v15, v32, 17, 1
	v_add3_u32 v10, v30, v10, s5
	v_add3_u32 v15, v32, v15, s5
	v_and_b32_e32 v10, 0xfffe0000, v10
	v_and_b32_e32 v15, 0xfffe0000, v15
	v_cvt_pk_bf16_f32 v22, v10, v15
	s_waitcnt lgkmcnt(1)
	v_bfe_u32 v10, v34, 17, 1
	s_waitcnt lgkmcnt(0)
	v_bfe_u32 v15, v36, 17, 1
	v_add3_u32 v10, v34, v10, s5
	v_add3_u32 v15, v36, v15, s5
	v_and_b32_e32 v10, 0xfffe0000, v10
	v_and_b32_e32 v15, 0xfffe0000, v15
	v_cvt_pk_bf16_f32 v23, v10, v15
	v_or_b32_e32 v10, s30, v13
	v_mul_lo_u32 v15, s27, v10
	v_mad_u64_u32 v[38:39], s[28:29], s26, v10, 0
	v_add3_u32 v39, v39, s31, v15
	v_bfe_u32 v10, v17, 17, 1
	v_bfe_u32 v15, v27, 17, 1
	v_add3_u32 v10, v17, v10, s5
	v_add3_u32 v15, v27, v15, s5
	v_lshl_add_u64 v[38:39], v[38:39], 1, v[24:25]
	v_and_b32_e32 v10, 0xfffe0000, v10
	v_and_b32_e32 v15, 0xfffe0000, v15
	global_store_dwordx4 v[38:39], v[20:23], off
	s_cmp_lt_i32 s42, 0xa400
	s_nop 0
	v_cvt_pk_bf16_f32 v20, v10, v15
	v_bfe_u32 v10, v11, 17, 1
	v_add3_u32 v10, v11, v10, s5
	v_bfe_u32 v11, v29, 17, 1
	v_add3_u32 v11, v29, v11, s5
	v_and_b32_e32 v10, 0xfffe0000, v10
	v_and_b32_e32 v11, 0xfffe0000, v11
	v_cvt_pk_bf16_f32 v21, v10, v11
	v_bfe_u32 v10, v31, 17, 1
	v_bfe_u32 v11, v33, 17, 1
	v_add3_u32 v10, v31, v10, s5
	v_add3_u32 v11, v33, v11, s5
	v_and_b32_e32 v10, 0xfffe0000, v10
	v_and_b32_e32 v11, 0xfffe0000, v11
	v_cvt_pk_bf16_f32 v22, v10, v11
	v_bfe_u32 v10, v35, 17, 1
	v_bfe_u32 v11, v37, 17, 1
	v_add3_u32 v10, v35, v10, s5
	v_add3_u32 v11, v37, v11, s5
	v_and_b32_e32 v10, 0xfffe0000, v10
	v_and_b32_e32 v11, 0xfffe0000, v11
	v_cvt_pk_bf16_f32 v23, v10, v11
	v_or_b32_e32 v10, s30, v14
	v_mul_lo_u32 v15, s27, v10
	v_mad_u64_u32 v[10:11], s[26:27], s26, v10, 0
	v_add3_u32 v11, v11, s31, v15
	v_lshl_add_u64 v[10:11], v[10:11], 1, v[24:25]
	global_store_dwordx4 v[10:11], v[20:23], off
	s_waitcnt lgkmcnt(0)
	s_cbranch_scc1 .LBB0_7
	s_branch .LBB0_38
